# MLA loop: row sums with scalar v_add_f32 instead of v_pk_add_f32 (packed f32 ops next to MFMAs)
# baseline (speedup 1.0000x reference)
; DI float xhalf_sum(float x) { const auto rr = __builtin_amdgcn_permlane32_swap(__float_as_uint(x), __float_as_uint(x), false, false); return __uint_as_float(rr[0]) + __uint_as_float(rr[1]); }
; template <int DQK, int DV, bool BAND> ...
;     ...
;       const float m_ref = (m_run == -INFINITY) ? 0.f : m_run;
;       float rs0 = 0.f, rs1 = 0.f;
; #pragma unroll
;       for (int r = 0; r < 16; ++r) { const float e0 = __builtin_amdgcn_exp2f(p0[r] - m_ref), e1 = __builtin_amdgcn_exp2f(p1[r] - m_ref); p0[r] = e0; p1[r] = e1; rs0 += e0; rs1 += e1; }
;       l_run += xhalf_sum(rs0 + rs1);
.LBB1_325:
	v_exp_f32_e32 v34, v34
	v_exp_f32_e32 v35, v35
	v_exp_f32_e32 v36, v36
	v_exp_f32_e32 v37, v37
	v_exp_f32_e32 v38, v38
	v_exp_f32_e32 v39, v39
	v_exp_f32_e32 v40, v40
	v_exp_f32_e32 v41, v41
	v_exp_f32_e32 v42, v42
	v_exp_f32_e32 v43, v43
	v_exp_f32_e32 v44, v44
	v_exp_f32_e32 v45, v45
	v_exp_f32_e32 v46, v46
	v_exp_f32_e32 v47, v47
	v_exp_f32_e32 v48, v48
	v_exp_f32_e32 v49, v49
	s_nop 0
	v_add_f32_e32 v168, v34, v36
	v_add_f32_e32 v169, v35, v37
	v_add_f32_e32 v170, v38, v40
	v_add_f32_e32 v171, v39, v41
	v_add_f32_e32 v168, v42, v168
	v_add_f32_e32 v169, v43, v169
	v_add_f32_e32 v170, v44, v170
	v_add_f32_e32 v171, v45, v171
	v_add_f32_e32 v168, v46, v168
	v_add_f32_e32 v169, v47, v169
	v_add_f32_e32 v170, v48, v170
	v_add_f32_e32 v171, v49, v171
	v_cvt_pk_bf16_f32 v34, v34, v35
	v_cvt_pk_bf16_f32 v35, v36, v37
	v_cvt_pk_bf16_f32 v36, v38, v39
	v_cvt_pk_bf16_f32 v37, v40, v41
	v_cvt_pk_bf16_f32 v38, v42, v43
	v_cvt_pk_bf16_f32 v39, v44, v45
	v_cvt_pk_bf16_f32 v40, v46, v47
	v_cvt_pk_bf16_f32 v41, v48, v49
	v_exp_f32_e32 v50, v50
	v_exp_f32_e32 v51, v51
	v_exp_f32_e32 v52, v52
	s_waitcnt lgkmcnt(0)
	v_mfma_f32_32x32x16_bf16 v[2:17], v[34:37], v[208:211], v[2:17]
	v_exp_f32_e32 v53, v53
	v_exp_f32_e32 v54, v54
	v_exp_f32_e32 v55, v55
	v_mfma_f32_32x32x16_bf16 v[18:33], v[34:37], v[212:215], v[18:33]
	v_exp_f32_e32 v56, v56
	v_exp_f32_e32 v57, v57
	v_exp_f32_e32 v58, v58
	v_mfma_f32_32x32x16_bf16 v[2:17], v[38:41], v[224:227], v[2:17]
	v_exp_f32_e32 v59, v59
	v_exp_f32_e32 v60, v60
	v_exp_f32_e32 v61, v61
	v_mfma_f32_32x32x16_bf16 v[18:33], v[38:41], v[228:231], v[18:33]
	v_exp_f32_e32 v62, v62
	v_exp_f32_e32 v63, v63
	v_exp_f32_e32 v64, v64
	v_exp_f32_e32 v65, v65
	s_nop 0
	v_add_f32_e32 v168, v50, v168
	v_add_f32_e32 v169, v51, v169
	v_add_f32_e32 v170, v52, v170
	v_add_f32_e32 v171, v53, v171
	v_add_f32_e32 v168, v54, v168
	v_add_f32_e32 v169, v55, v169
	v_add_f32_e32 v170, v56, v170
	v_add_f32_e32 v171, v57, v171
	v_add_f32_e32 v168, v58, v168
	v_add_f32_e32 v169, v59, v169
	v_add_f32_e32 v170, v60, v170
	v_add_f32_e32 v171, v61, v171
	v_add_f32_e32 v168, v62, v168
	v_add_f32_e32 v169, v63, v169
	v_add_f32_e32 v170, v64, v170
	v_add_f32_e32 v171, v65, v171
	v_cvt_pk_bf16_f32 v50, v50, v51
	v_cvt_pk_bf16_f32 v51, v52, v53
	v_cvt_pk_bf16_f32 v52, v54, v55
	v_cvt_pk_bf16_f32 v53, v56, v57
	v_cvt_pk_bf16_f32 v54, v58, v59
	v_cvt_pk_bf16_f32 v55, v60, v61
	v_cvt_pk_bf16_f32 v56, v62, v63
	v_cvt_pk_bf16_f32 v57, v64, v65
	v_add_f32_e32 v168, v168, v170
	v_add_f32_e32 v169, v169, v171
	v_mfma_f32_32x32x16_bf16 v[2:17], v[50:53], v[216:219], v[2:17]
	v_add_f32_e32 v168, v168, v169
	v_mov_b32_e32 v169, v168
	v_mfma_f32_32x32x16_bf16 v[18:33], v[50:53], v[220:223], v[18:33]
	s_nop 0
	v_permlane32_swap_b32_e32 v168, v169
	v_mfma_f32_32x32x16_bf16 v[2:17], v[54:57], v[232:235], v[2:17]
	v_add_f32_e32 v168, v168, v169
	v_add_f32_e32 v126, v126, v168
	v_mfma_f32_32x32x16_bf16 v[18:33], v[54:57], v[236:239], v[18:33]
	s_add_u32 s12, s12, s8
	s_addc_u32 s13, s13, s9
	s_add_u32 s14, s14, s10
	s_addc_u32 s15, s15, s11
	s_cmp_eq_u32 s75, s21
	s_cbranch_scc1 .LBB1_327
	v_mov_b32_e32 v133, v0
	s_branch .LBB1_318
